# mixer1 prompt units: gate-multiply operands (bias + eight gate loads) fetched before the chunk MFMA loop
# baseline (speedup 1.0000x reference)
; __device__ __forceinline__ unsigned pk2(float lo, float hi) { return pg8::cvt_pk_bf16(lo, hi); }
; __device__ __forceinline__ void phase_mixer1(const Params& p, LAS unsigned char* lds) {
;     ...
;             {
;                 const int sub = lane >> 4, c8 = (lane & 15) * 8; float g8[8], b8[8]; load8f(lng + g * 128 + c8, g8); load8f(lnb + g * 128 + c8, b8);
; #pragma unroll
;                 for (int ps = 0; ps < 4; ++ps) {
;                     const int t = 16 * wave + 4 * ps + sub; const float mean = stats[2 * t], rstd = stats[2 * t + 1];
;                     float x[8]; unpack8(*(const v4u*)(Z + (row0 + t) * NZ1 + 1024 + g * 128 + c8), x);
; #pragma unroll
;                     for (int q = 0; q < 8; ++q) { const float vn = (x[q] - mean) * rstd * g8[q] + b8[q]; vnT[vnt_off(c8 + q, t)] = (unsigned short)(pk2(vn, 0.f) & 0xffffu); }
;                 }
;             }
.LBB0_878:
	s_or_b64 exec, exec, s[6:7]
	s_lshr_b32 s6, s78, 7
	s_and_b32 s7, s6, 2
	v_lshl_add_u64 v[2:3], s[0:1], 0, v[118:119]
	v_mov_b64_e32 v[0:1], s[34:35]
	s_add_i32 s7, s7, s78
	v_mad_u64_u32 v[4:5], s[16:17], v2, s65, v[0:1]
	s_and_b32 s28, s7, 3
	v_mov_b32_e32 v2, v5
	s_lshl_b32 s40, s28, 9
	v_mad_u64_u32 v[2:3], s[16:17], v3, s65, v[2:3]
	v_lshl_add_u64 v[6:7], v[92:93], 0, s[40:41]
	v_lshl_add_u64 v[8:9], v[94:95], 0, s[40:41]
	v_mov_b32_e32 v5, v2
	s_lshl_b32 s40, s28, 8
	v_lshl_add_u64 v[2:3], v[4:5], 0, s[40:41]
	v_mov_b32_e32 v139, v79
	v_lshl_add_u64 v[2:3], v[2:3], 0, v[138:139]
	s_waitcnt lgkmcnt(0)
	s_barrier
	global_load_dwordx4 v[2:5], v[2:3], off offset:2048
	s_nop 0
	global_load_dwordx4 v[28:31], v[8:9], off
	global_load_dwordx4 v[36:39], v[6:7], off
	global_load_dwordx4 v[32:35], v[6:7], off offset:16
	global_load_dwordx4 v[24:27], v[8:9], off offset:16
	v_lshl_add_u64 v[242:243], s[0:1], 0, v[120:121]
	v_mad_u64_u32 v[244:245], s[16:17], v242, s65, v[0:1]
	v_mov_b32_e32 v242, v245
	v_mad_u64_u32 v[242:243], s[16:17], v243, s65, v[242:243]
	v_mov_b32_e32 v245, v242
	v_lshl_add_u64 v[242:243], v[244:245], 0, s[40:41]
	v_lshl_add_u64 v[242:243], v[242:243], 0, v[138:139]
	global_load_dwordx4 v[226:229], v[242:243], off offset:2048
	v_lshl_add_u64 v[242:243], s[0:1], 0, v[122:123]
	v_mad_u64_u32 v[244:245], s[16:17], v242, s65, v[0:1]
	v_mov_b32_e32 v242, v245
	v_mad_u64_u32 v[242:243], s[16:17], v243, s65, v[242:243]
	v_mov_b32_e32 v245, v242
	v_lshl_add_u64 v[242:243], v[244:245], 0, s[40:41]
	v_lshl_add_u64 v[242:243], v[242:243], 0, v[138:139]
	global_load_dwordx4 v[230:233], v[242:243], off offset:2048
	v_lshl_add_u64 v[242:243], s[0:1], 0, v[124:125]
	v_mad_u64_u32 v[244:245], s[16:17], v242, s65, v[0:1]
	v_mov_b32_e32 v242, v245
	v_mad_u64_u32 v[242:243], s[16:17], v243, s65, v[242:243]
	v_mov_b32_e32 v245, v242
	v_lshl_add_u64 v[242:243], v[244:245], 0, s[40:41]
	v_lshl_add_u64 v[242:243], v[242:243], 0, v[138:139]
	global_load_dwordx4 v[234:237], v[242:243], off offset:2048
	v_lshl_add_u64 v[8:9], s[0:1], 0, v[120:121]
	ds_read_b64 v[6:7], v197
	v_mad_u64_u32 v[10:11], s[16:17], v8, s65, v[0:1]
	v_mov_b32_e32 v8, v11
	v_mad_u64_u32 v[8:9], s[16:17], v9, s65, v[8:9]
	v_mov_b32_e32 v11, v8
	v_lshl_add_u64 v[8:9], v[10:11], 0, s[40:41]
	v_lshl_add_u64 v[8:9], v[8:9], 0, v[138:139]
	s_andn2_b64 vcc, exec, s[18:19]
	s_waitcnt vmcnt(7)
	v_lshlrev_b32_e32 v10, 16, v2
	v_and_b32_e32 v2, 0xffff0000, v2
	v_lshlrev_b32_e32 v11, 16, v3
	v_and_b32_e32 v3, 0xffff0000, v3
	v_lshlrev_b32_e32 v12, 16, v4
	v_and_b32_e32 v4, 0xffff0000, v4
	v_lshlrev_b32_e32 v13, 16, v5
	v_and_b32_e32 v5, 0xffff0000, v5
	s_waitcnt lgkmcnt(0)
	v_sub_f32_e32 v10, v10, v6
	v_sub_f32_e32 v2, v2, v6
	v_sub_f32_e32 v11, v11, v6
	v_sub_f32_e32 v3, v3, v6
	v_sub_f32_e32 v12, v12, v6
	v_sub_f32_e32 v4, v4, v6
	v_sub_f32_e32 v13, v13, v6
	v_sub_f32_e32 v5, v5, v6
	v_mul_f32_e32 v6, v7, v10
	v_mul_f32_e32 v2, v7, v2
	s_waitcnt vmcnt(5)
	v_fma_f32 v6, v36, v6, v28
	v_fma_f32 v2, v37, v2, v29
	v_mul_f32_e32 v10, v7, v11
	v_cvt_pk_bf16_f32 v6, v6, v79
	ds_write_b16 v147, v6 offset:1024
	v_cvt_pk_bf16_f32 v2, v2, v79
	v_mul_f32_e32 v3, v7, v3
	v_mul_f32_e32 v11, v7, v12
	v_mul_f32_e32 v4, v7, v4
	v_mul_f32_e32 v12, v7, v13
	v_mul_f32_e32 v5, v7, v5
	v_fma_f32 v7, v38, v10, v30
	ds_write_b16 v148, v2 offset:1024
	v_cvt_pk_bf16_f32 v2, v7, v79
	v_fma_f32 v3, v39, v3, v31
	ds_write_b16 v149, v2 offset:1024
	v_cvt_pk_bf16_f32 v2, v3, v79
	s_waitcnt vmcnt(3)
	v_fma_f32 v10, v32, v11, v24
	ds_write_b16 v150, v2 offset:1024
	v_cvt_pk_bf16_f32 v2, v10, v79
	v_fma_f32 v4, v33, v4, v25
	ds_write_b16 v151, v2 offset:1024
	v_cvt_pk_bf16_f32 v2, v4, v79
	v_fma_f32 v11, v34, v12, v26
	v_fma_f32 v5, v35, v5, v27
	ds_write_b16 v152, v2 offset:1024
	v_cvt_pk_bf16_f32 v2, v11, v79
	ds_write_b16 v153, v2 offset:1024
	v_cvt_pk_bf16_f32 v10, v5, v79
	v_lshl_add_u64 v[6:7], s[0:1], 0, v[122:123]
	v_mad_u64_u32 v[8:9], s[16:17], v6, s65, v[0:1]
	v_mov_b32_e32 v6, v9
	v_mad_u64_u32 v[6:7], s[16:17], v7, s65, v[6:7]
	v_mov_b32_e32 v9, v6
	v_lshl_add_u64 v[6:7], v[8:9], 0, s[40:41]
	ds_read_b64 v[8:9], v198
	ds_write_b16 v154, v10 offset:1024
	v_lshl_add_u64 v[6:7], v[6:7], 0, v[138:139]
	s_waitcnt vmcnt(2)
	v_mov_b32_e32 v2, v226
	v_mov_b32_e32 v3, v227
	v_mov_b32_e32 v4, v228
	v_mov_b32_e32 v5, v229
	v_lshlrev_b32_e32 v10, 16, v2
	v_and_b32_e32 v2, 0xffff0000, v2
	v_lshlrev_b32_e32 v11, 16, v3
	v_and_b32_e32 v3, 0xffff0000, v3
	v_lshlrev_b32_e32 v12, 16, v4
	v_and_b32_e32 v4, 0xffff0000, v4
	v_lshlrev_b32_e32 v13, 16, v5
	v_and_b32_e32 v5, 0xffff0000, v5
	s_waitcnt lgkmcnt(1)
	v_sub_f32_e32 v10, v10, v8
	v_sub_f32_e32 v2, v2, v8
	v_sub_f32_e32 v11, v11, v8
	v_sub_f32_e32 v3, v3, v8
	v_sub_f32_e32 v12, v12, v8
	v_sub_f32_e32 v4, v4, v8
	v_sub_f32_e32 v13, v13, v8
	v_sub_f32_e32 v5, v5, v8
	v_mul_f32_e32 v8, v9, v10
	v_mul_f32_e32 v2, v9, v2
	v_fma_f32 v8, v36, v8, v28
	v_fma_f32 v2, v37, v2, v29
	v_mul_f32_e32 v10, v9, v11
	v_cvt_pk_bf16_f32 v8, v8, v79
	ds_write_b16 v155, v8 offset:1024
	v_cvt_pk_bf16_f32 v2, v2, v79
	v_mul_f32_e32 v3, v9, v3
	v_mul_f32_e32 v11, v9, v12
	v_mul_f32_e32 v4, v9, v4
	v_mul_f32_e32 v12, v9, v13
	v_mul_f32_e32 v5, v9, v5
	v_fma_f32 v9, v38, v10, v30
	ds_write_b16 v156, v2 offset:1024
	v_cvt_pk_bf16_f32 v2, v9, v79
	v_fma_f32 v3, v39, v3, v31
	ds_write_b16 v157, v2 offset:1024
	v_cvt_pk_bf16_f32 v2, v3, v79
	v_fma_f32 v10, v32, v11, v24
	ds_write_b16 v158, v2 offset:1024
	v_cvt_pk_bf16_f32 v2, v10, v79
	v_fma_f32 v4, v33, v4, v25
	ds_write_b16 v159, v2 offset:1024
	v_cvt_pk_bf16_f32 v2, v4, v79
	v_fma_f32 v11, v34, v12, v26
	v_fma_f32 v5, v35, v5, v27
	ds_write_b16 v160, v2 offset:1024
	v_cvt_pk_bf16_f32 v2, v11, v79
	ds_write_b16 v161, v2 offset:1024
	v_cvt_pk_bf16_f32 v8, v5, v79
	v_lshl_add_u64 v[6:7], s[0:1], 0, v[124:125]
	v_mad_u64_u32 v[0:1], s[16:17], v6, s65, v[0:1]
	v_mov_b32_e32 v6, v1
	v_mad_u64_u32 v[6:7], s[16:17], v7, s65, v[6:7]
	v_mov_b32_e32 v1, v6
	ds_read_b64 v[6:7], v199
	ds_write_b16 v162, v8 offset:1024
	v_lshl_add_u64 v[0:1], v[0:1], 0, s[40:41]
	v_lshl_add_u64 v[0:1], v[0:1], 0, v[138:139]
	s_waitcnt vmcnt(1)
; #define LAS __attribute__((address_space(3)))
; __device__ __forceinline__ unsigned pk2(float lo, float hi) { return pg8::cvt_pk_bf16(lo, hi); }
; __device__ __forceinline__ void phase_mixer1(const Params& p, LAS unsigned char* lds) {
;     ...
;                     float x[8]; unpack8(*(const v4u*)(Z + (row0 + t) * NZ1 + 1024 + g * 128 + c8), x);
; #pragma unroll
;                     for (int q = 0; q < 8; ++q) { const float vn = (x[q] - mean) * rstd * g8[q] + b8[q]; vnT[vnt_off(c8 + q, t)] = (unsigned short)(pk2(vn, 0.f) & 0xffffu); }
;                 }
;             }
;             __syncthreads();
;             {
;                 const int fr = lane & 15, fq = lane >> 4, t = 16 * wave + fr;
;                 f32x4 acc[8];
; #pragma unroll
;                 for (int n = 0; n < 8; ++n) acc[n] = (f32x4){0.f, 0.f, 0.f, 0.f};
;                 const bf16* wrow = Wm + (size_t)g * 16384 + t * 128;
;                 const int ksteps = (wave >> 1) + 1;
;                 for (int k = 0; k < ksteps; ++k) {
;                     const bf16x8 bfrag = *(const bf16x8*)(wrow + k * 32 + fq * 8);
; #pragma unroll
;                     for (int n = 0; n < 8; ++n) { const bf16x8 afrag = *(const LAS bf16x8*)(vnT + vnt_off(n * 16 + fr, k * 32 + fq * 8)); acc[n] = __builtin_amdgcn_mfma_f32_16x16x32_bf16(afrag, bfrag, acc[n], 0, 0, 0); }
;                 }
;                 const float bs = sgb[g * 128 + t];
; #pragma unroll
;                 for (int n = 0; n < 8; ++n) {
;                     const int col = g * 128 + n * 16 + 4 * fq; const v2u uw = *(const v2u*)(Z + (row0 + t) * NZ1 + 512 + col);
	v_mov_b32_e32 v2, v230
	v_mov_b32_e32 v3, v231
	v_mov_b32_e32 v4, v232
	v_mov_b32_e32 v5, v233
	v_lshlrev_b32_e32 v8, 16, v2
	v_and_b32_e32 v2, 0xffff0000, v2
	v_lshlrev_b32_e32 v9, 16, v3
	v_and_b32_e32 v3, 0xffff0000, v3
	v_lshlrev_b32_e32 v10, 16, v4
	v_and_b32_e32 v4, 0xffff0000, v4
	v_lshlrev_b32_e32 v11, 16, v5
	v_and_b32_e32 v5, 0xffff0000, v5
	s_waitcnt lgkmcnt(1)
	v_sub_f32_e32 v8, v8, v6
	v_sub_f32_e32 v2, v2, v6
	v_sub_f32_e32 v9, v9, v6
	v_sub_f32_e32 v3, v3, v6
	v_sub_f32_e32 v10, v10, v6
	v_sub_f32_e32 v4, v4, v6
	v_sub_f32_e32 v11, v11, v6
	v_sub_f32_e32 v5, v5, v6
	v_mul_f32_e32 v6, v7, v8
	v_mul_f32_e32 v2, v7, v2
	v_fma_f32 v6, v36, v6, v28
	v_fma_f32 v2, v37, v2, v29
	v_mul_f32_e32 v8, v7, v9
	v_cvt_pk_bf16_f32 v6, v6, v79
	ds_write_b16 v163, v6 offset:1024
	v_cvt_pk_bf16_f32 v2, v2, v79
	v_mul_f32_e32 v3, v7, v3
	v_mul_f32_e32 v9, v7, v10
	v_mul_f32_e32 v4, v7, v4
	v_mul_f32_e32 v10, v7, v11
	v_mul_f32_e32 v5, v7, v5
	v_fma_f32 v7, v38, v8, v30
	ds_write_b16 v164, v2 offset:1024
	v_cvt_pk_bf16_f32 v2, v7, v79
	v_fma_f32 v3, v39, v3, v31
	ds_write_b16 v165, v2 offset:1024
	v_cvt_pk_bf16_f32 v2, v3, v79
	v_fma_f32 v8, v32, v9, v24
	ds_write_b16 v166, v2 offset:1024
	v_cvt_pk_bf16_f32 v2, v8, v79
	v_fma_f32 v4, v33, v4, v25
	ds_write_b16 v167, v2 offset:1024
	v_cvt_pk_bf16_f32 v2, v4, v79
	v_fma_f32 v9, v34, v10, v26
	v_fma_f32 v5, v35, v5, v27
	ds_write_b16 v168, v2 offset:1024
	v_cvt_pk_bf16_f32 v2, v9, v79
	ds_write_b16 v169, v2 offset:1024
	v_cvt_pk_bf16_f32 v44, v5, v79
	ds_read_b64 v[52:53], v200
	ds_write_b16 v170, v44 offset:1024
	v_mov_b32_e32 v3, 0
	v_mov_b32_e32 v2, v3
	v_mov_b32_e32 v1, v3
	v_mov_b32_e32 v0, v3
	v_mov_b32_e32 v7, v3
	v_mov_b32_e32 v6, v3
	v_mov_b32_e32 v5, v3
	v_mov_b32_e32 v4, v3
	v_mov_b32_e32 v11, v3
	v_mov_b32_e32 v10, v3
	v_mov_b32_e32 v9, v3
	v_mov_b32_e32 v8, v3
	v_mov_b32_e32 v15, v3
	v_mov_b32_e32 v14, v3
	v_mov_b32_e32 v13, v3
	v_mov_b32_e32 v12, v3
	v_mov_b32_e32 v19, v3
	v_mov_b32_e32 v18, v3
	v_mov_b32_e32 v17, v3
	v_mov_b32_e32 v16, v3
	v_mov_b32_e32 v23, v3
	v_mov_b32_e32 v22, v3
	v_mov_b32_e32 v21, v3
	v_mov_b32_e32 v20, v3
	v_mov_b32_e32 v43, v3
	v_mov_b32_e32 v42, v3
	v_mov_b32_e32 v41, v3
	v_mov_b32_e32 v40, v3
	v_mov_b32_e32 v47, v3
	v_mov_b32_e32 v46, v3
	v_mov_b32_e32 v45, v3
	s_waitcnt vmcnt(0)
	v_mov_b32_e32 v48, v234
	v_mov_b32_e32 v49, v235
	v_mov_b32_e32 v50, v236
	v_mov_b32_e32 v51, v237
	v_lshlrev_b32_e32 v44, 16, v48
	s_waitcnt lgkmcnt(1)
	v_sub_f32_e32 v44, v44, v52
	v_and_b32_e32 v48, 0xffff0000, v48
	v_mul_f32_e32 v44, v53, v44
	v_lshlrev_b32_e32 v54, 16, v49
	v_lshlrev_b32_e32 v55, 16, v50
	v_sub_f32_e32 v48, v48, v52
	v_fma_f32 v28, v36, v44, v28
	v_and_b32_e32 v49, 0xffff0000, v49
	v_and_b32_e32 v50, 0xffff0000, v50
	v_lshlrev_b32_e32 v56, 16, v51
	v_and_b32_e32 v51, 0xffff0000, v51
	v_sub_f32_e32 v54, v54, v52
	v_sub_f32_e32 v55, v55, v52
	v_mul_f32_e32 v48, v53, v48
	v_cvt_pk_bf16_f32 v28, v28, v79
	v_sub_f32_e32 v49, v49, v52
	v_sub_f32_e32 v50, v50, v52
	v_sub_f32_e32 v56, v56, v52
	v_sub_f32_e32 v51, v51, v52
	v_mul_f32_e32 v52, v53, v54
	v_mul_f32_e32 v54, v53, v55
	v_fma_f32 v29, v37, v48, v29
	ds_write_b16 v171, v28 offset:1024
	v_cvt_pk_bf16_f32 v28, v29, v79
	v_mul_f32_e32 v49, v53, v49
	v_fma_f32 v30, v38, v52, v30
	v_fma_f32 v24, v32, v54, v24
	ds_write_b16 v172, v28 offset:1024
	v_cvt_pk_bf16_f32 v28, v30, v79
	v_mul_f32_e32 v50, v53, v50
	v_fmac_f32_e32 v31, v39, v49
	ds_write_b16 v173, v28 offset:1024
	v_cvt_pk_bf16_f32 v28, v31, v79
	ds_write_b16 v174, v28 offset:1024
	v_cvt_pk_bf16_f32 v24, v24, v79
	v_mul_f32_e32 v55, v53, v56
	v_fma_f32 v25, v33, v50, v25
	ds_write_b16 v175, v24 offset:1024
	v_cvt_pk_bf16_f32 v24, v25, v79
	v_mul_f32_e32 v51, v53, v51
	v_fma_f32 v26, v34, v55, v26
	ds_write_b16 v176, v24 offset:1024
	v_cvt_pk_bf16_f32 v24, v26, v79
	v_mov_b32_e32 v44, v3
	v_fmac_f32_e32 v27, v35, v51
	ds_write_b16 v177, v24 offset:1024
	v_cvt_pk_bf16_f32 v24, v27, v79
	ds_write_b16 v178, v24 offset:1024
	s_lshl_b32 s90, s28, 7
	v_readlane_b32 s84, v254, 9
	v_readlane_b32 s85, v254, 10
	v_add_u32_e32 v242, s90, v96
	v_ashrrev_i32_e32 v243, 31, v242
	v_lshl_add_u64 v[242:243], v[242:243], 2, s[84:85]
	global_load_dword v246, v[242:243], off
	v_lshl_add_u64 v[242:243], s[0:1], 0, v[96:97]
	v_mov_b64_e32 v[244:245], s[34:35]
	v_mad_u64_u32 v[244:245], s[86:87], v242, s65, v[244:245]
	v_mov_b32_e32 v250, v245
	v_mad_u64_u32 v[250:251], s[86:87], v243, s65, v[250:251]
	v_mov_b32_e32 v245, v250
	v_or_b32_e32 v250, s90, v144
	v_lshlrev_b32_e32 v250, 1, v250
	v_mov_b32_e32 v251, 0
	v_lshl_add_u64 v[244:245], v[244:245], 0, v[250:251]
	global_load_dwordx2 v[248:249], v[244:245], off offset:1024
	global_load_dwordx2 v[226:227], v[244:245], off offset:1056
	global_load_dwordx2 v[228:229], v[244:245], off offset:1088
	global_load_dwordx2 v[230:231], v[244:245], off offset:1120
	global_load_dwordx2 v[232:233], v[244:245], off offset:1152
	global_load_dwordx2 v[234:235], v[244:245], off offset:1184
	global_load_dwordx2 v[236:237], v[244:245], off offset:1216
	global_load_dwordx2 v[240:241], v[244:245], off offset:1248
	s_waitcnt lgkmcnt(0)
	s_barrier
	s_cbranch_vccnz .LBB0_881
	s_and_b32 s6, s6, 0x1fffffe
	s_add_i32 s6, s6, s77
	s_and_b32 s6, s6, 3
	s_lshl_b32 s40, s6, 15
	v_mov_b32_e32 v44, 0
	v_lshl_add_u64 v[24:25], v[136:137], 0, s[40:41]
	v_mov_b32_e32 v26, v143
	s_mov_b32 s6, s64
	v_mov_b32_e32 v45, v44
	v_mov_b32_e32 v46, v44
	v_mov_b32_e32 v47, v44
	v_mov_b32_e32 v40, v44
	v_mov_b32_e32 v41, v44
	v_mov_b32_e32 v42, v44
	v_mov_b32_e32 v43, v44
	v_mov_b32_e32 v20, v44
	v_mov_b32_e32 v21, v44
	v_mov_b32_e32 v22, v44
	v_mov_b32_e32 v23, v44
	v_mov_b32_e32 v16, v44
	v_mov_b32_e32 v17, v44
	v_mov_b32_e32 v18, v44
	v_mov_b32_e32 v19, v44
	v_mov_b32_e32 v12, v44
	v_mov_b32_e32 v13, v44
	v_mov_b32_e32 v14, v44
	v_mov_b32_e32 v15, v44
	v_mov_b32_e32 v8, v44
	v_mov_b32_e32 v9, v44
	v_mov_b32_e32 v10, v44
	v_mov_b32_e32 v11, v44
	v_mov_b32_e32 v4, v44
	v_mov_b32_e32 v5, v44
	v_mov_b32_e32 v6, v44
	v_mov_b32_e32 v7, v44
	v_mov_b32_e32 v0, v44
	v_mov_b32_e32 v1, v44
	v_mov_b32_e32 v2, v44
	v_mov_b32_e32 v3, v44

; __device__ __forceinline__ unsigned pk2(float lo, float hi) { return pg8::cvt_pk_bf16(lo, hi); }
; __device__ __forceinline__ void phase_mixer1(const Params& p, LAS unsigned char* lds) {
;     ...
;                 const float bs = sgb[g * 128 + t];
; #pragma unroll
;                 for (int n = 0; n < 8; ++n) {
;                     const int col = g * 128 + n * 16 + 4 * fq; const v2u uw = *(const v2u*)(Z + (row0 + t) * NZ1 + 512 + col);
;                     const float u0 = __uint_as_float(uw.x << 16), u1 = __uint_as_float(uw.x & 0xffff0000u), u2 = __uint_as_float(uw.y << 16), u3 = __uint_as_float(uw.y & 0xffff0000u);
;                     v2u o; o.x = pk2(u0 * (acc[n][0] + bs), u1 * (acc[n][1] + bs)); o.y = pk2(u2 * (acc[n][2] + bs), u3 * (acc[n][3] + bs));
;                     *(v2u*)(Y + (row0 + t) * D + 512 + col) = o;
;                 }
.LBB0_881:
	s_lshl_b32 s6, s28, 7
	s_mov_b32 s17, s89
	s_mov_b32 s16, s88
	v_add_u32_e32 v24, s6, v96
	v_readlane_b32 s80, v254, 5
	v_ashrrev_i32_e32 v25, 31, v24
	v_readlane_b32 s84, v254, 9
	v_readlane_b32 s85, v254, 10
	v_mov_b64_e32 v[26:27], s[34:35]
	v_or_b32_e32 v30, s6, v144
	v_lshl_add_u64 v[24:25], v[24:25], 2, s[84:85]
	v_lshl_add_u64 v[24:25], s[0:1], 0, v[96:97]
	v_mad_u64_u32 v[26:27], s[0:1], v24, s65, v[26:27]
	v_mov_b32_e32 v28, v27
	v_mad_u64_u32 v[28:29], s[0:1], v25, s65, v[28:29]
	v_mov_b32_e32 v27, v28
	v_lshlrev_b32_e32 v78, 1, v30
	v_lshl_add_u64 v[26:27], v[26:27], 0, v[78:79]
	v_lshlrev_b64 v[24:25], 11, v[24:25]
	v_lshl_add_u64 v[24:25], s[36:37], 0, v[24:25]
	v_lshl_add_u64 v[24:25], v[24:25], 0, v[78:79]
	s_add_i32 s40, s9, s8
	v_or_b32_e32 v140, s40, v145
	s_mul_hi_i32 s53, s50, 0x600000
	s_cmp_lt_i32 s28, 2
	s_mul_i32 s52, s50, 0x600000
	v_readlane_b32 s81, v254, 6
	v_readlane_b32 s82, v254, 7
	v_readlane_b32 s83, v254, 8
	v_readlane_b32 s86, v254, 11
	v_readlane_b32 s87, v254, 12
	v_readlane_b32 s88, v254, 13
	v_readlane_b32 s89, v254, 14
	v_readlane_b32 s90, v254, 15
	v_readlane_b32 s91, v254, 16
	v_readlane_b32 s92, v254, 17
	v_readlane_b32 s93, v254, 18
	v_readlane_b32 s94, v254, 19
	v_readlane_b32 s95, v254, 20
	s_waitcnt vmcnt(8)
	v_mov_b32_e32 v32, v246
	v_add_f32_e32 v30, v44, v32
	v_add_f32_e32 v31, v45, v32
	v_add_f32_e32 v33, v46, v32
	v_add_f32_e32 v34, v47, v32
	v_add_f32_e32 v20, v20, v32
	v_add_f32_e32 v21, v21, v32
	v_add_f32_e32 v22, v22, v32
	v_add_f32_e32 v23, v23, v32
	v_add_f32_e32 v16, v16, v32
	v_add_f32_e32 v17, v17, v32
	s_waitcnt vmcnt(7)
	v_mov_b32_e32 v28, v248
	v_mov_b32_e32 v29, v249
	v_lshlrev_b32_e32 v35, 16, v28
	v_and_b32_e32 v28, 0xffff0000, v28
	v_lshlrev_b32_e32 v36, 16, v29
	v_and_b32_e32 v29, 0xffff0000, v29
	v_mul_f32_e32 v30, v30, v35
	v_mul_f32_e32 v28, v31, v28
	v_mul_f32_e32 v31, v33, v36
	v_mul_f32_e32 v29, v34, v29
	v_cvt_pk_bf16_f32 v28, v30, v28
	v_cvt_pk_bf16_f32 v29, v31, v29
	v_add_f32_e32 v33, v40, v32
	v_add_f32_e32 v34, v41, v32
	v_add_f32_e32 v35, v42, v32
	v_add_f32_e32 v36, v43, v32
	global_store_dwordx2 v[24:25], v[28:29], off offset:1024
	v_add_f32_e32 v18, v18, v32
	v_add_f32_e32 v19, v19, v32
	v_add_f32_e32 v12, v12, v32
	v_add_f32_e32 v13, v13, v32
	v_add_f32_e32 v14, v14, v32
	v_add_f32_e32 v15, v15, v32
	v_add_f32_e32 v8, v8, v32
	v_add_f32_e32 v9, v9, v32
	v_add_f32_e32 v10, v10, v32
	v_add_f32_e32 v11, v11, v32
	v_add_f32_e32 v4, v4, v32
	v_add_f32_e32 v5, v5, v32
	v_add_f32_e32 v6, v6, v32
	v_add_f32_e32 v7, v7, v32
	v_add_f32_e32 v0, v32, v0
	v_add_f32_e32 v1, v32, v1
	v_add_f32_e32 v2, v32, v2
	v_add_f32_e32 v3, v32, v3
	s_waitcnt vmcnt(7)
	v_mov_b32_e32 v30, v226
	v_mov_b32_e32 v31, v227
	v_lshlrev_b32_e32 v28, 16, v30
	v_and_b32_e32 v29, 0xffff0000, v30
	v_lshlrev_b32_e32 v30, 16, v31
	v_and_b32_e32 v31, 0xffff0000, v31
	v_mul_f32_e32 v28, v33, v28
	v_mul_f32_e32 v29, v34, v29
	v_mul_f32_e32 v30, v35, v30
	v_mul_f32_e32 v31, v36, v31
	v_cvt_pk_bf16_f32 v28, v28, v29
	v_cvt_pk_bf16_f32 v29, v30, v31
	s_nop 0
	global_store_dwordx2 v[24:25], v[28:29], off offset:1056
	s_waitcnt vmcnt(7)
	v_mov_b32_e32 v30, v228
	v_mov_b32_e32 v31, v229
	v_lshlrev_b32_e32 v28, 16, v30
	v_and_b32_e32 v29, 0xffff0000, v30
	v_lshlrev_b32_e32 v30, 16, v31
	v_and_b32_e32 v31, 0xffff0000, v31
	v_mul_f32_e32 v20, v20, v28
	v_mul_f32_e32 v21, v21, v29
	v_mul_f32_e32 v22, v22, v30
	v_mul_f32_e32 v23, v23, v31
	v_cvt_pk_bf16_f32 v20, v20, v21
	v_cvt_pk_bf16_f32 v21, v22, v23
	s_nop 0
	global_store_dwordx2 v[24:25], v[20:21], off offset:1088
	s_waitcnt vmcnt(7)
	v_mov_b32_e32 v22, v230
	v_mov_b32_e32 v23, v231
	v_lshlrev_b32_e32 v20, 16, v22
	v_and_b32_e32 v21, 0xffff0000, v22
	v_lshlrev_b32_e32 v22, 16, v23
	v_and_b32_e32 v23, 0xffff0000, v23
	v_mul_f32_e32 v16, v16, v20
	v_mul_f32_e32 v17, v17, v21
	v_mul_f32_e32 v18, v18, v22
	v_mul_f32_e32 v19, v19, v23
	v_cvt_pk_bf16_f32 v16, v16, v17
	v_cvt_pk_bf16_f32 v17, v18, v19
	s_nop 0
	global_store_dwordx2 v[24:25], v[16:17], off offset:1120
	s_waitcnt vmcnt(7)
	v_mov_b32_e32 v18, v232
	v_mov_b32_e32 v19, v233
	v_lshlrev_b32_e32 v16, 16, v18
	v_and_b32_e32 v17, 0xffff0000, v18
	v_lshlrev_b32_e32 v18, 16, v19
	v_and_b32_e32 v19, 0xffff0000, v19
	v_mul_f32_e32 v12, v12, v16
	v_mul_f32_e32 v13, v13, v17
	v_mul_f32_e32 v14, v14, v18
	v_mul_f32_e32 v15, v15, v19
	v_cvt_pk_bf16_f32 v12, v12, v13
	v_cvt_pk_bf16_f32 v13, v14, v15
	s_nop 0
	global_store_dwordx2 v[24:25], v[12:13], off offset:1152
	s_waitcnt vmcnt(7)
	v_mov_b32_e32 v14, v234
	v_mov_b32_e32 v15, v235
	v_lshlrev_b32_e32 v12, 16, v14
	v_and_b32_e32 v13, 0xffff0000, v14
	v_lshlrev_b32_e32 v14, 16, v15
	v_and_b32_e32 v15, 0xffff0000, v15
	v_mul_f32_e32 v8, v8, v12
	v_mul_f32_e32 v9, v9, v13
	v_mul_f32_e32 v10, v10, v14
	v_mul_f32_e32 v11, v11, v15
	v_cvt_pk_bf16_f32 v8, v8, v9
	v_cvt_pk_bf16_f32 v9, v10, v11
	s_nop 0
	global_store_dwordx2 v[24:25], v[8:9], off offset:1184
	s_waitcnt vmcnt(7)
	v_mov_b32_e32 v10, v236
	v_mov_b32_e32 v11, v237
	v_lshlrev_b32_e32 v8, 16, v10
	v_and_b32_e32 v9, 0xffff0000, v10
	v_lshlrev_b32_e32 v10, 16, v11
	v_and_b32_e32 v11, 0xffff0000, v11
	v_mul_f32_e32 v4, v4, v8
	v_mul_f32_e32 v5, v5, v9
	v_mul_f32_e32 v6, v6, v10
	v_mul_f32_e32 v7, v7, v11
	v_cvt_pk_bf16_f32 v4, v4, v5
	v_cvt_pk_bf16_f32 v5, v6, v7
	s_nop 0
	global_store_dwordx2 v[24:25], v[4:5], off offset:1216
	s_waitcnt vmcnt(7)
	v_mov_b32_e32 v6, v240
	v_mov_b32_e32 v7, v241
	v_lshlrev_b32_e32 v4, 16, v6
	v_and_b32_e32 v5, 0xffff0000, v6
	v_lshlrev_b32_e32 v6, 16, v7
	v_and_b32_e32 v7, 0xffff0000, v7
	v_mul_f32_e32 v0, v0, v4
	v_mul_f32_e32 v1, v1, v5
	v_mul_f32_e32 v2, v2, v6
	v_mul_f32_e32 v3, v3, v7
	v_cvt_pk_bf16_f32 v0, v0, v1
	v_cvt_pk_bf16_f32 v1, v2, v3
	global_store_dwordx2 v[24:25], v[0:1], off offset:1248
	s_cbranch_scc1 .LBB0_915
	s_cmp_gt_i32 s28, 2
	s_mov_b32 s88, s16
	s_mov_b32 s89, s17
	s_cbranch_scc0 .LBB0_916
	v_lshl_add_u64 v[4:5], v[98:99], 0, s[52:53]
	v_cmp_lt_i32_e32 vcc, 14, v140
	v_mov_b32_e32 v0, 0
	v_mov_b32_e32 v8, 0
	v_mov_b32_e32 v9, 0
	v_mov_b32_e32 v10, 0
	v_mov_b32_e32 v11, 0
	s_and_saveexec_b64 s[0:1], vcc
	s_cbranch_execz .LBB0_885
	v_add_u32_e32 v1, -15, v140
	v_mad_u64_u32 v[2:3], s[6:7], v1, s65, v[4:5]
	global_load_dwordx4 v[8:11], v[2:3], off
